# gla_c q/k/v stage thread mapping: one load covers 32 rows x 32 B instead of 64 rows x 16 B, LDS bank spread unchanged
# baseline (speedup 1.0000x reference)
.LBB0_816:
	s_cmp_lt_i32 s56, 6
	s_cselect_b64 s[2:3], -1, 0
	s_and_b64 s[66:67], s[2:3], s[0:1]
	s_andn2_b64 vcc, exec, s[66:67]
	s_cbranch_vccnz .LBB0_856
	s_cmpk_lt_i32 s33, 0x800
	v_and_b32_e32 v84, 15, v145
	v_lshrrev_b32_e32 v35, 7, v145
	v_lshrrev_b32_e32 v85, 3, v145
	s_cbranch_scc0 .LBB0_832
	s_add_u32 s68, s54, 0x6800000
	s_waitcnt lgkmcnt(0)
	v_lshrrev_b32_e32 v1, 4, v144
	v_readlane_b32 s45, v244, 6
	s_addc_u32 s69, s55, 0
	v_lshlrev_b32_e32 v0, 3, v1
	s_lshr_b32 s0, s45, 8
	v_readlane_b32 s44, v244, 25
	v_lshrrev_b32_e32 v2, 5, v144
	s_lshl_b32 s1, s44, 5
	v_cmp_eq_u32_e64 s[2:3], s0, v2
	v_lshlrev_b32_e32 v1, 2, v1
	v_and_b32_e32 v2, 8, v0
	v_mov_b32_e32 v31, 0
	s_lshl_b32 s78, s0, 9
	v_lshl_or_b32 v4, s0, 6, v1
	v_lshl_or_b32 v30, s0, 4, v2
	s_and_b32 s0, s1, 0x60
	v_lshlrev_b64 v[2:3], 11, v[30:31]
	v_or_b32_e32 v34, s0, v84
	s_movk_i32 s0, 0x204
	v_lshl_add_u64 v[32:33], s[88:89], 0, v[2:3]
	v_mul_lo_u32 v7, v4, s0
	v_and_b32_e32 v2, 0x7f, v145
	v_and_b32_e32 v4, 1, v35
	v_mul_u32_u24_e32 v6, 0x8100, v4
	v_lshlrev_b32_e32 v2, 2, v2
	v_add3_u32 v8, 0, v6, v2
	v_cmp_eq_u32_e64 s[4:5], 0, v4
	v_cmp_eq_u32_e64 s[6:7], 1, v4
	v_and_b32_e32 v6, 0x300, v145
	v_lshlrev_b32_e32 v4, 7, v4
	v_sub_u32_e32 v4, v4, v6
	v_lshlrev_b32_e32 v4, 2, v4
	s_add_i32 s8, 0, 0x10600
	s_add_i32 s12, 0, 0x10200
	v_lshrrev_b32_e32 v5, 8, v145
	v_add3_u32 v88, s8, v4, v2
	v_lshl_add_u32 v89, v145, 2, s12
	v_lshrrev_b32_e32 v2, 7, v145
	v_lshlrev_b32_e32 v2, 4, v2
	v_and_b32_e32 v135, 1, v145
	v_lshl_add_u32 v2, v135, 3, v2
	v_bfe_u32 v134, v145, 6, 1
	v_lshlrev_b32_e32 v134, 5, v134
	v_bfe_u32 v135, v145, 1, 5
	v_add_u32_e32 v134, v134, v135
	v_mad_u32_u24 v4, v134, s0, 0
	v_or_b32_e32 v6, 7, v2
	s_lshl_b32 s12, s44, 3
	v_mul_u32_u24_e32 v9, 0x4080, v5
	v_cmp_eq_u32_e64 s[8:9], 1, v5
	v_mul_u32_u24_e32 v5, 0x110, v134
	s_add_i32 s42, 0, 0x12800
	v_lshl_add_u32 v90, v2, 2, v4
	v_lshl_add_u32 v91, v6, 2, v4
	v_lshlrev_b32_e32 v4, 1, v2
	s_and_b32 s12, s12, 0x1ffffff0
	s_movk_i32 s0, 0x110
	v_add3_u32 v92, s42, v5, v4
	v_or_b32_e32 v4, s12, v84
	v_mul_lo_u32 v4, v4, s0
	v_and_b32_e32 v5, 48, v144
	s_add_i32 s13, s12, 0x80
	v_add3_u32 v93, s42, v4, v5
	v_or_b32_e32 v4, s13, v84
	v_mul_lo_u32 v4, v4, s0
	v_mul_u32_u24_e32 v12, 0x90, v6
	v_add3_u32 v94, s42, v4, v5
	v_or_b32_e32 v4, s12, v1
	v_and_or_b32 v6, s1, 32, v84
	v_mul_u32_u24_e32 v13, 0x110, v6
	v_or_b32_e32 v15, 1, v4
	v_or_b32_e32 v16, 2, v4
	v_or_b32_e32 v17, 3, v4
	s_bfe_u32 s0, s45, 0x20006
	s_lshl_b32 s1, s44, 4
	s_movk_i32 s43, 0x90
	v_add3_u32 v95, s42, v13, v5
	v_lshl_add_u32 v13, v6, 1, 0
	v_cmp_gt_u32_e64 s[12:13], v6, v4
	v_cmp_lt_u32_e64 s[14:15], v6, v4
	v_cmp_gt_u32_e64 s[16:17], v6, v15
	v_cmp_gt_u32_e64 s[18:19], v6, v16
	v_cmp_lt_u32_e64 s[20:21], v6, v16
	v_cmp_gt_u32_e64 s[22:23], v6, v17
	v_cmp_lt_u32_e64 s[24:25], v6, v17
	v_or_b32_e32 v6, 16, v6
	v_lshl_or_b32 v97, s0, 4, v84
	s_and_b32 s44, s1, 0x3fffffc0
	v_mul_lo_u32 v14, v4, s43
	v_cmp_gt_u32_e64 s[26:27], v6, v4
	v_cmp_lt_u32_e64 s[28:29], v6, v4
	v_mul_u32_u24_e32 v4, 0x110, v97
	v_or_b32_e32 v30, s44, v84
	v_add3_u32 v98, s42, v4, v5
	v_or_b32_e32 v4, 16, v30
	v_mov_b32_e32 v5, v31
	v_cmp_gt_u32_e64 s[30:31], v6, v15
	v_cmp_gt_u32_e64 s[34:35], v6, v16
	v_cmp_lt_u32_e64 s[36:37], v6, v16
	v_cmp_gt_u32_e64 s[38:39], v6, v17
	v_cmp_lt_u32_e64 s[40:41], v6, v17
	v_lshlrev_b64 v[38:39], 8, v[4:5]
	v_or_b32_e32 v4, s44, v1
	v_or3_b32 v6, v1, s1, 48
	v_mbcnt_lo_u32_b32 v1, -1, 0
	v_mbcnt_hi_u32_b32 v1, -1, v1
	v_and_b32_e32 v20, 64, v1
	v_xor_b32_e32 v19, 16, v1
	v_add_u32_e32 v20, 64, v20
	v_cmp_lt_i32_e32 vcc, v19, v20
	v_mul_lo_u32 v18, v30, s43
	v_lshlrev_b64 v[36:37], 8, v[30:31]
	v_or_b32_e32 v30, 32, v30
	s_lshl_b32 s0, s0, 6
	v_cndmask_b32_e32 v19, v1, v19, vcc
	v_lshlrev_b64 v[40:41], 8, v[30:31]
	v_or3_b32 v30, v144, s1, 48
	s_and_b32 s45, s45, 0xffffff00
	s_add_i32 s0, s0, 0
	v_lshlrev_b32_e32 v101, 2, v19
	v_xor_b32_e32 v19, 32, v1
	v_and_b32_e32 v16, 48, v145
	v_mul_lo_u32 v5, v30, s43
	v_lshlrev_b64 v[42:43], 8, v[30:31]
	s_add_i32 s45, s0, s45
	v_lshlrev_b32_e32 v30, 2, v4
	v_cmp_lt_i32_e32 vcc, v19, v20
	v_lshl_add_u32 v3, v34, 2, 0
	s_movk_i32 s10, 0x100
	v_lshl_add_u32 v10, v134, 1, 0
	v_mul_u32_u24_e32 v11, 0x90, v2
	v_mad_u32_u24 v15, v97, s43, 0
	v_add_u32_e32 v17, 0, v16
	s_add_u32 s72, s54, 0x4400000
	v_lshl_add_u64 v[44:45], s[92:93], 0, v[30:31]
	v_lshlrev_b32_e32 v30, 2, v6
	v_cndmask_b32_e32 v1, v1, v19, vcc
	s_mov_b32 s71, 0
	v_or_b32_e32 v86, 0x80, v145
	v_and_b32_e32 v87, 0x37f, v145
	v_cmp_gt_u32_e64 s[10:11], s10, v145
	v_add_u32_e32 v96, 0x1100, v95
	v_cmp_gt_u32_e64 s[42:43], 16, v144
	v_lshl_add_u32 v99, v144, 2, s45
	v_lshl_add_u32 v100, v84, 2, s0
	s_addc_u32 s73, s55, 0
	v_lshl_add_u64 v[46:47], s[92:93], 0, v[30:31]
	v_lshlrev_b32_e32 v102, 2, v1
	s_movk_i32 s79, 0x2600
	s_mov_b32 s80, 0xbfb8aa3b
	s_mov_b32 s81, 0x800000
	s_mov_b32 s82, 0x3f317217
	s_mov_b32 s83, 0x7f800000
	v_lshlrev_b32_e32 v48, 1, v2
	s_mov_b32 s74, 0x3db504f3
	v_add_u32_e32 v103, v10, v11
	v_add_u32_e32 v104, v10, v12
	v_add_u32_e32 v105, v13, v14
	v_add_u32_e32 v106, v15, v16
	v_lshlrev_b32_e32 v30, 1, v0
	v_add_u32_e32 v107, v17, v18
	v_add_u32_e32 v108, v17, v5
	v_mov_b32_e32 v109, 0x358637bd
	s_mov_b64 s[76:77], 0x1140
	v_lshlrev_b32_e32 v50, 1, v4
	v_lshlrev_b32_e32 v52, 1, v6
	v_mov_b32_e32 v110, 0x41b17218
	v_add_u32_e32 v111, v3, v7
	v_add_u32_e32 v112, v8, v9
	s_mov_b32 s84, s33
	global_load_dwordx4 v[212:215], v[44:45], off
	global_load_dwordx4 v[216:219], v[44:45], off offset:64
	global_load_dwordx4 v[220:223], v[44:45], off offset:128
	global_load_dwordx4 v[224:227], v[46:47], off
	s_waitcnt vmcnt(0)
	s_branch .LBB0_820
